# v29: v25 + compression phase: workgroups on odd XCDs run their compression-MLP items before the memory-bound chunk-state carry, the others after it
# baseline (speedup 1.0000x reference)
.LBB0_1055:
	s_cmp_lt_i32 s96, 6
	s_cselect_b64 s[80:81], -1, 0
	s_and_b64 s[0:1], s[80:81], s[0:1]
	s_andn2_b64 vcc, exec, s[0:1]
	s_cbranch_vccnz .LBB0_1221
	s_mov_b32 s101, 0
.Lcfin_pre:
	v_writelane_b32 v238, s80, 36
	s_mov_b32 s2, s94
	s_lshl_b32 s33, s94, 3
	v_writelane_b32 v238, s81, 37
	v_writelane_b32 v238, s92, 38
	s_ashr_i32 s0, s94, 4
	s_and_b32 s1, s33, 0x78
	v_writelane_b32 v238, s93, 39
	v_writelane_b32 v238, s2, 40
	s_mov_b32 s43, 0
	s_waitcnt vmcnt(0)
	v_mbcnt_hi_u32_b32 v6, -1, v216
	v_writelane_b32 v238, s3, 41
	v_mov_b32_e32 v7, 0
	v_readlane_b32 s2, v238, 3
	s_add_i32 s42, s2, s1
	s_ashr_i32 s1, s0, 31
	s_lshl_b64 s[2:3], s[0:1], 22
	s_add_u32 s2, s90, s2
	s_addc_u32 s3, s91, s3
	s_lshl_b64 s[38:39], s[42:43], 9
	s_add_u32 s2, s2, s38
	s_addc_u32 s3, s3, s39
	s_add_u32 s2, s2, 0x3ebf1600
	s_addc_u32 s3, s3, 0
	v_writelane_b32 v238, s2, 8
	s_nop 1
	v_writelane_b32 v238, s3, 9
	s_lshl_b64 s[2:3], s[0:1], 15
	s_add_u32 s2, s90, s2
	s_addc_u32 s3, s91, s3
	s_lshl_b32 s4, s42, 2
	s_add_u32 s34, s2, s4
	s_addc_u32 s35, s3, 0
	s_add_u32 s6, s34, 0x42bf1600
	s_addc_u32 s7, s35, 0
	s_lshl_b64 s[2:3], s[0:1], 21
	s_add_u32 s36, s90, s2
	s_addc_u32 s37, s91, s3
	s_add_u32 s2, s34, 0x42bf2600
	s_addc_u32 s3, s35, 0
	v_writelane_b32 v238, s2, 10
	s_nop 1
	v_writelane_b32 v238, s3, 11
	s_add_u32 s2, s34, 0x42bf2800
	s_addc_u32 s3, s35, 0
	v_writelane_b32 v238, s2, 12
	s_nop 1
	v_writelane_b32 v238, s3, 13
	s_add_u32 s2, s34, 0x42bf2a00
	s_addc_u32 s3, s35, 0
	v_writelane_b32 v238, s2, 14
	s_nop 1
	v_writelane_b32 v238, s3, 15
	s_add_u32 s2, s34, 0x42bf2c00
	s_addc_u32 s3, s35, 0
	v_writelane_b32 v238, s2, 16
	s_nop 1
	v_writelane_b32 v238, s3, 17
	s_add_u32 s2, s34, 0x42bf2e00
	s_addc_u32 s3, s35, 0
	v_writelane_b32 v238, s2, 18
	s_nop 1
	v_writelane_b32 v238, s3, 19
	s_add_u32 s2, s34, 0x42bf3000
	s_addc_u32 s3, s35, 0
	v_writelane_b32 v238, s2, 20
	s_nop 1
	v_writelane_b32 v238, s3, 21
	s_add_u32 s2, s34, 0x42bf3200
	s_addc_u32 s3, s35, 0
	v_writelane_b32 v238, s2, 34
	s_nop 1
	v_writelane_b32 v238, s3, 35
	s_add_u32 s2, s34, 0x42bf3400
	s_addc_u32 s3, s35, 0
	v_writelane_b32 v238, s2, 22
	s_nop 1
	v_writelane_b32 v238, s3, 23
	s_add_u32 s2, s34, 0x42bf3600
	s_addc_u32 s3, s35, 0
	v_writelane_b32 v238, s2, 24
	s_nop 1
	v_writelane_b32 v238, s3, 25
	s_add_u32 s2, s34, 0x42bf3800
	s_addc_u32 s3, s35, 0
	v_writelane_b32 v238, s2, 26
	s_nop 1
	v_writelane_b32 v238, s3, 27
	s_add_u32 s2, s34, 0x42bf3a00
	s_addc_u32 s3, s35, 0
	v_writelane_b32 v238, s2, 28
	s_nop 1
	v_writelane_b32 v238, s3, 29
	s_add_u32 s2, s34, 0x42bf3c00
	s_addc_u32 s3, s35, 0
	v_writelane_b32 v238, s2, 30
	s_nop 1
	v_writelane_b32 v238, s3, 31
	s_add_u32 s2, s34, 0x42bf3e00
	s_addc_u32 s3, s35, 0
	v_writelane_b32 v238, s2, 32
	s_nop 1
	v_writelane_b32 v238, s3, 33
	s_add_u32 s2, s34, 0x42bf4000
	s_addc_u32 s3, s35, 0
	v_writelane_b32 v238, s2, 42
	s_nop 1
	v_writelane_b32 v238, s3, 43
	s_add_u32 s2, s34, 0x42bf4200
	s_addc_u32 s3, s35, 0
	v_writelane_b32 v238, s2, 44
	s_nop 1
	v_writelane_b32 v238, s3, 45
	s_add_u32 s2, s34, 0x42bf4400
	s_addc_u32 s3, s35, 0
	s_add_u32 s48, s34, 0x42bf4600
	s_addc_u32 s49, s35, 0
	s_add_u32 s50, s34, 0x42bf4800
	s_addc_u32 s51, s35, 0
	s_add_u32 s54, s34, 0x42bf4a00
	s_addc_u32 s55, s35, 0
	s_add_u32 s60, s34, 0x42bf4c00
	s_addc_u32 s61, s35, 0
	s_add_u32 s62, s34, 0x42bf4e00
	s_addc_u32 s63, s35, 0
	s_add_u32 s64, s34, 0x42bf5000
	s_addc_u32 s65, s35, 0
	s_add_u32 s70, s34, 0x42bf5200
	s_addc_u32 s71, s35, 0
	s_add_u32 s78, s34, 0x42bf5400
	s_addc_u32 s79, s35, 0
	s_add_u32 s80, s34, 0x42bf5600
	s_addc_u32 s81, s35, 0
	s_add_u32 s82, s34, 0x42bf5800
	s_addc_u32 s83, s35, 0
	s_add_u32 s86, s34, 0x42bf5a00
	s_addc_u32 s87, s35, 0
	s_add_u32 s96, s34, 0x42bf5c00
	s_addc_u32 s97, s35, 0
	s_add_u32 s8, s34, 0x42bf5e00
	s_addc_u32 s9, s35, 0
	s_add_u32 s94, s34, 0x42bf6000
	s_addc_u32 s95, s35, 0
	s_add_u32 s40, s34, 0x42bf6200
	s_addc_u32 s41, s35, 0
	s_add_u32 s44, s34, 0x42bf6400
	s_addc_u32 s45, s35, 0
	s_add_u32 s52, s34, 0x42bf6600
	s_addc_u32 s53, s35, 0
	s_add_u32 s72, s34, 0x42bf6800
	s_addc_u32 s73, s35, 0
	s_add_u32 s74, s34, 0x42bf6a00
	s_addc_u32 s75, s35, 0
	s_add_u32 s76, s34, 0x42bf6c00
	s_addc_u32 s77, s35, 0
	s_add_u32 s84, s34, 0x42bf6e00
	s_addc_u32 s85, s35, 0
	s_add_u32 s92, s34, 0x42bf7000
	v_writelane_b32 v238, s2, 46
	s_addc_u32 s93, s35, 0
	s_nop 0
	v_writelane_b32 v238, s3, 47
	s_add_u32 s2, s34, 0x42bf7200
	s_addc_u32 s3, s35, 0
	s_add_u32 s56, s34, 0x42bf7400
	s_addc_u32 s57, s35, 0
	s_add_u32 s58, s34, 0x42bf7600
	s_addc_u32 s59, s35, 0
	s_add_u32 s66, s34, 0x42bf7800
	s_addc_u32 s67, s35, 0
	s_add_u32 s68, s34, 0x42bf7a00
	s_addc_u32 s69, s35, 0
	s_add_u32 s4, s34, 0x42bf7c00
	s_addc_u32 s5, s35, 0
	s_add_u32 s10, s34, 0x42bf7e00
	s_addc_u32 s11, s35, 0
	s_add_u32 s12, s34, 0x42bf8000
	s_addc_u32 s13, s35, 0
	s_add_u32 s14, s34, 0x42bf8200
	s_addc_u32 s15, s35, 0
	s_add_u32 s16, s34, 0x42bf8400
	s_addc_u32 s17, s35, 0
	s_add_u32 s18, s34, 0x42bf8600
	s_addc_u32 s19, s35, 0
	s_add_u32 s20, s34, 0x42bf8800
	s_addc_u32 s21, s35, 0
	s_add_u32 s22, s34, 0x42bf8a00
	s_addc_u32 s23, s35, 0
	s_add_u32 s24, s34, 0x42bf8c00
	s_addc_u32 s25, s35, 0
	s_add_u32 s26, s34, 0x42bf8e00
	s_addc_u32 s27, s35, 0
	s_add_u32 s28, s34, 0x42bf9000
	s_addc_u32 s29, s35, 0
	s_add_u32 s30, s34, 0x42bf9200
	s_addc_u32 s31, s35, 0
	s_add_u32 s34, s34, 0x42bf9400
	s_addc_u32 s35, s35, 0
	s_lshl_b64 s[46:47], s[42:43], 8
	s_add_u32 s36, s36, s46
	s_addc_u32 s37, s37, s47
	s_add_u32 s36, s36, 0x42c71600
	s_addc_u32 s37, s37, 0
	s_lshl_b64 s[0:1], s[0:1], 16
	s_add_u32 s0, s88, s0
	s_addc_u32 s1, s89, s1
	s_add_u32 s0, s0, s38
	s_addc_u32 s1, s1, s39
	s_add_u32 s38, s0, 0x8500000
	s_addc_u32 s39, s1, 0
	s_movk_i32 s42, 0x7fff
	s_mov_b64 s[46:47], -1
	s_bitcmp1_b32 s94, 0
	s_cbranch_scc0 .LBB0_1057
	s_cmp_eq_u32 s101, 0
	s_cbranch_scc1 .Lc_items_first
.LBB0_1057:
	v_add_u32_e32 v2, s43, v6
	v_cndmask_b32_e64 v0, 0, 1, s[46:47]
	v_ashrrev_i32_e32 v3, 31, v2
	v_readlane_b32 s46, v238, 8
	v_cmp_ne_u32_e64 s[0:1], 1, v0
	v_lshlrev_b64 v[0:1], 2, v[2:3]
	v_readlane_b32 s47, v238, 9
	v_lshl_add_u64 v[2:3], v[2:3], 1, s[36:37]
	s_mov_b32 s43, 0x10000
	v_lshl_add_u64 v[4:5], s[46:47], 0, v[0:1]
	v_add_co_u32_e32 v8, vcc, 0x10000, v4
	global_load_dword v130, v[4:5], off
	global_load_dword v133, v7, s[6:7]
	v_addc_co_u32_e32 v9, vcc, 0, v5, vcc
	global_load_dword v128, v[8:9], off
	global_load_dword v132, v7, s[6:7] offset:512
	v_add_co_u32_e32 v8, vcc, 0x20000, v4
	v_readlane_b32 s46, v238, 10
	s_nop 0
	v_addc_co_u32_e32 v9, vcc, 0, v5, vcc
	global_load_dword v126, v[8:9], off
	global_load_dword v131, v7, s[6:7] offset:1024
	v_add_co_u32_e32 v8, vcc, 0x30000, v4
	v_readlane_b32 s47, v238, 11
	s_nop 0
	v_addc_co_u32_e32 v9, vcc, 0, v5, vcc
	global_load_dword v124, v[8:9], off
	global_load_dword v129, v7, s[6:7] offset:1536
	v_add_co_u32_e32 v8, vcc, 0x40000, v4
	v_lshl_add_u64 v[0:1], s[38:39], 0, v[0:1]
	s_nop 0
	v_addc_co_u32_e32 v9, vcc, 0, v5, vcc
	global_load_dword v122, v[8:9], off
	global_load_dword v127, v7, s[6:7] offset:2048
	v_add_co_u32_e32 v8, vcc, 0x50000, v4
	s_waitcnt vmcnt(0)
	v_fmac_f32_e32 v130, 0, v133
	v_addc_co_u32_e32 v9, vcc, 0, v5, vcc
	global_load_dword v120, v[8:9], off
	global_load_dword v125, v7, s[6:7] offset:2560
	v_add_co_u32_e32 v8, vcc, 0x60000, v4
	v_bfe_u32 v133, v130, 16, 1
	s_nop 0
	v_addc_co_u32_e32 v9, vcc, 0, v5, vcc
	global_load_dword v118, v[8:9], off
	global_load_dword v123, v7, s[6:7] offset:3072
	v_add_co_u32_e32 v8, vcc, 0x70000, v4
	v_fmac_f32_e32 v128, v130, v132
	s_nop 0
	v_addc_co_u32_e32 v9, vcc, 0, v5, vcc
	global_load_dword v116, v[8:9], off
	global_load_dword v121, v7, s[6:7] offset:3584
	v_add_co_u32_e32 v8, vcc, 0x80000, v4
	global_load_dword v119, v7, s[46:47]
	s_nop 0
	v_addc_co_u32_e32 v9, vcc, 0, v5, vcc
	global_load_dword v113, v[8:9], off
	v_add_co_u32_e32 v8, vcc, 0x90000, v4
	v_readlane_b32 s46, v238, 12
	s_nop 0
	v_addc_co_u32_e32 v9, vcc, 0, v5, vcc
	v_readlane_b32 s47, v238, 13
	global_load_dword v111, v[8:9], off
	v_add3_u32 v133, v130, v133, s42
	v_bfe_u32 v130, v128, 16, 1
	v_add3_u32 v130, v128, v130, s42
	v_fmac_f32_e32 v126, v128, v131
	global_load_dword v117, v7, s[46:47]
	v_add_co_u32_e32 v8, vcc, 0xa0000, v4
	v_readlane_b32 s46, v238, 14
	s_nop 0
	v_addc_co_u32_e32 v9, vcc, 0, v5, vcc
	v_readlane_b32 s47, v238, 15
	global_load_dword v109, v[8:9], off
	v_bfe_u32 v128, v126, 16, 1
	v_add3_u32 v128, v126, v128, s42
	v_fmac_f32_e32 v124, v126, v129
	v_bfe_u32 v126, v124, 16, 1
	global_load_dword v115, v7, s[46:47]
	v_add_co_u32_e32 v8, vcc, 0xb0000, v4
	v_readlane_b32 s46, v238, 16
	s_nop 0
	v_addc_co_u32_e32 v9, vcc, 0, v5, vcc
	v_readlane_b32 s47, v238, 17
	global_load_dword v107, v[8:9], off
	v_add3_u32 v126, v124, v126, s42
	v_fmac_f32_e32 v122, v124, v127
	v_bfe_u32 v124, v122, 16, 1
	v_add3_u32 v124, v122, v124, s42
	global_load_dword v114, v7, s[46:47]
	v_add_co_u32_e32 v8, vcc, 0xc0000, v4
	v_readlane_b32 s46, v238, 18
	s_nop 0
	v_addc_co_u32_e32 v9, vcc, 0, v5, vcc
	v_readlane_b32 s47, v238, 19
	global_load_dword v105, v[8:9], off
	s_waitcnt vmcnt(0)
	v_fmac_f32_e32 v120, v122, v125
	s_nop 1
	global_load_dword v112, v7, s[46:47]
	v_add_co_u32_e32 v8, vcc, 0xd0000, v4
	v_readlane_b32 s46, v238, 20
	s_nop 0
	v_addc_co_u32_e32 v9, vcc, 0, v5, vcc
	v_readlane_b32 s47, v238, 21
	global_load_dword v103, v[8:9], off
	v_bfe_u32 v122, v120, 16, 1
	v_add3_u32 v122, v120, v122, s42
	v_fmac_f32_e32 v118, v120, v123
	v_bfe_u32 v120, v118, 16, 1
	global_load_dword v110, v7, s[46:47]
	v_add_co_u32_e32 v8, vcc, 0xe0000, v4
	v_readlane_b32 s46, v238, 34
	s_nop 0
	v_addc_co_u32_e32 v9, vcc, 0, v5, vcc
	v_readlane_b32 s47, v238, 35
	global_load_dword v101, v[8:9], off
	v_add3_u32 v120, v118, v120, s42
	v_fmac_f32_e32 v116, v118, v121
	v_bfe_u32 v118, v116, 16, 1
	v_add3_u32 v118, v116, v118, s42
	global_load_dword v108, v7, s[46:47]
	v_add_co_u32_e32 v8, vcc, 0xf0000, v4
	v_readlane_b32 s46, v238, 22
	s_nop 0
	v_addc_co_u32_e32 v9, vcc, 0, v5, vcc
	v_readlane_b32 s47, v238, 23
	global_load_dword v99, v[8:9], off
	v_fmac_f32_e32 v113, v116, v119
	v_bfe_u32 v116, v113, 16, 1
	v_add3_u32 v116, v113, v116, s42
	v_fmac_f32_e32 v111, v113, v117
	global_load_dword v106, v7, s[46:47]
	v_add_co_u32_e32 v8, vcc, 0x100000, v4
	v_readlane_b32 s46, v238, 24
	s_nop 0
	v_addc_co_u32_e32 v9, vcc, 0, v5, vcc
	v_readlane_b32 s47, v238, 25
	global_load_dword v97, v[8:9], off
	v_bfe_u32 v113, v111, 16, 1
	v_add3_u32 v113, v111, v113, s42
	v_fmac_f32_e32 v109, v111, v115
	v_bfe_u32 v111, v109, 16, 1
	global_load_dword v104, v7, s[46:47]
	v_add_co_u32_e32 v8, vcc, 0x110000, v4
	v_readlane_b32 s46, v238, 26
	s_nop 0
	v_addc_co_u32_e32 v9, vcc, 0, v5, vcc
	v_readlane_b32 s47, v238, 27
	global_load_dword v95, v[8:9], off
	v_fmac_f32_e32 v107, v109, v114
	v_add3_u32 v111, v109, v111, s42
	v_bfe_u32 v109, v107, 16, 1
	v_add3_u32 v109, v107, v109, s42
	global_load_dword v102, v7, s[46:47]
	v_add_co_u32_e32 v8, vcc, 0x120000, v4
	v_readlane_b32 s46, v238, 28
	s_nop 0
	v_addc_co_u32_e32 v9, vcc, 0, v5, vcc
	v_readlane_b32 s47, v238, 29
	global_load_dword v93, v[8:9], off
	s_waitcnt vmcnt(0)
	v_fmac_f32_e32 v105, v107, v112
	s_nop 1
	global_load_dword v100, v7, s[46:47]
	v_add_co_u32_e32 v8, vcc, 0x130000, v4
	v_readlane_b32 s46, v238, 30
	s_nop 0
	v_addc_co_u32_e32 v9, vcc, 0, v5, vcc
	v_readlane_b32 s47, v238, 31
	global_load_dword v91, v[8:9], off
	v_bfe_u32 v107, v105, 16, 1
	v_add3_u32 v107, v105, v107, s42
	v_fmac_f32_e32 v103, v105, v110
	s_nop 0
	global_load_dword v98, v7, s[46:47]
	v_add_co_u32_e32 v8, vcc, 0x140000, v4
	v_readlane_b32 s46, v238, 32
	s_nop 0
	v_addc_co_u32_e32 v9, vcc, 0, v5, vcc
	v_readlane_b32 s47, v238, 33
	global_load_dword v89, v[8:9], off
	v_bfe_u32 v105, v103, 16, 1
	v_add3_u32 v105, v103, v105, s42
	v_fmac_f32_e32 v101, v103, v108
	s_nop 0
	global_load_dword v96, v7, s[46:47]
	v_add_co_u32_e32 v8, vcc, 0x150000, v4
	v_readlane_b32 s46, v238, 42
	s_nop 0
	v_addc_co_u32_e32 v9, vcc, 0, v5, vcc
	v_readlane_b32 s47, v238, 43
	global_load_dword v88, v[8:9], off
	v_bfe_u32 v103, v101, 16, 1
	v_add3_u32 v103, v101, v103, s42
	v_fmac_f32_e32 v99, v101, v106
	s_nop 0
	global_load_dword v94, v7, s[46:47]
	v_add_co_u32_e32 v8, vcc, 0x160000, v4
	v_readlane_b32 s46, v238, 44
	s_nop 0
	v_addc_co_u32_e32 v9, vcc, 0, v5, vcc
	v_readlane_b32 s47, v238, 45
	global_load_dword v86, v[8:9], off
	v_bfe_u32 v101, v99, 16, 1
	v_add3_u32 v101, v99, v101, s42
	v_fmac_f32_e32 v97, v99, v104
	s_nop 0
	global_load_dword v92, v7, s[46:47]
	v_add_co_u32_e32 v8, vcc, 0x170000, v4
	v_readlane_b32 s46, v238, 46
	s_nop 0
	v_addc_co_u32_e32 v9, vcc, 0, v5, vcc
	v_readlane_b32 s47, v238, 47
	global_load_dword v84, v[8:9], off
	v_bfe_u32 v99, v97, 16, 1
	v_add3_u32 v99, v97, v99, s42
	v_fmac_f32_e32 v95, v97, v102
	s_nop 0
	global_load_dword v90, v7, s[46:47]
	v_add_co_u32_e32 v8, vcc, 0x180000, v4
	v_bfe_u32 v97, v95, 16, 1
	s_nop 0
	v_addc_co_u32_e32 v9, vcc, 0, v5, vcc
	global_load_dword v82, v[8:9], off
	global_load_dword v87, v7, s[48:49]
	v_add_co_u32_e32 v8, vcc, 0x190000, v4
	v_add3_u32 v97, v95, v97, s42
	s_nop 0
	v_addc_co_u32_e32 v9, vcc, 0, v5, vcc
	global_load_dword v80, v[8:9], off
	global_load_dword v85, v7, s[50:51]
	v_add_co_u32_e32 v8, vcc, 0x1a0000, v4
	s_mov_b64 s[46:47], 0
	s_nop 0
	v_addc_co_u32_e32 v9, vcc, 0, v5, vcc
	global_load_dword v78, v[8:9], off
	global_load_dword v83, v7, s[54:55]
	v_add_co_u32_e32 v8, vcc, 0x1b0000, v4
	s_waitcnt vmcnt(0)
	v_fmac_f32_e32 v93, v95, v100
	v_addc_co_u32_e32 v9, vcc, 0, v5, vcc
	global_load_dword v76, v[8:9], off
	global_load_dword v81, v7, s[60:61]
	v_add_co_u32_e32 v8, vcc, 0x1c0000, v4
	v_bfe_u32 v95, v93, 16, 1
	s_nop 0
	v_addc_co_u32_e32 v9, vcc, 0, v5, vcc
	global_load_dword v74, v[8:9], off
	global_load_dword v79, v7, s[62:63]
	v_add_co_u32_e32 v8, vcc, 0x1d0000, v4
	v_fmac_f32_e32 v91, v93, v98
	s_nop 0
	v_addc_co_u32_e32 v9, vcc, 0, v5, vcc
	global_load_dword v72, v[8:9], off
	global_load_dword v77, v7, s[64:65]
	v_add_co_u32_e32 v8, vcc, 0x1e0000, v4
	v_add3_u32 v95, v93, v95, s42
	s_nop 0
	v_addc_co_u32_e32 v9, vcc, 0, v5, vcc
	global_load_dword v70, v[8:9], off
	global_load_dword v75, v7, s[70:71]
	v_add_co_u32_e32 v8, vcc, 0x1f0000, v4
	v_bfe_u32 v93, v91, 16, 1
	s_nop 0
	v_addc_co_u32_e32 v9, vcc, 0, v5, vcc
	global_load_dword v68, v[8:9], off
	global_load_dword v73, v7, s[78:79]
	v_add_co_u32_e32 v8, vcc, 0x200000, v4
	v_fmac_f32_e32 v89, v91, v96
	s_nop 0
	v_addc_co_u32_e32 v9, vcc, 0, v5, vcc
	global_load_dword v66, v[8:9], off
	global_load_dword v71, v7, s[80:81]
	v_add_co_u32_e32 v8, vcc, 0x210000, v4
	v_add3_u32 v93, v91, v93, s42
	s_nop 0
	v_addc_co_u32_e32 v9, vcc, 0, v5, vcc
	global_load_dword v64, v[8:9], off
	global_load_dword v69, v7, s[82:83]
	v_add_co_u32_e32 v8, vcc, 0x220000, v4
	v_bfe_u32 v91, v89, 16, 1
	s_nop 0
	v_addc_co_u32_e32 v9, vcc, 0, v5, vcc
	global_load_dword v62, v[8:9], off
	global_load_dword v67, v7, s[86:87]
	v_add_co_u32_e32 v8, vcc, 0x230000, v4
	v_fmac_f32_e32 v88, v89, v94
	s_nop 0
	v_addc_co_u32_e32 v9, vcc, 0, v5, vcc
	global_load_dword v60, v[8:9], off
	global_load_dword v65, v7, s[96:97]
	v_add_co_u32_e32 v8, vcc, 0x240000, v4
	v_add3_u32 v91, v89, v91, s42
	s_nop 0
	v_addc_co_u32_e32 v9, vcc, 0, v5, vcc
	global_load_dword v58, v[8:9], off
	global_load_dword v63, v7, s[8:9]
	v_add_co_u32_e32 v8, vcc, 0x250000, v4
	v_bfe_u32 v89, v88, 16, 1
	s_nop 0
	v_addc_co_u32_e32 v9, vcc, 0, v5, vcc
	global_load_dword v56, v[8:9], off
	global_load_dword v61, v7, s[94:95]
	v_add_co_u32_e32 v8, vcc, 0x260000, v4
	v_fmac_f32_e32 v86, v88, v92
	s_nop 0
	v_addc_co_u32_e32 v9, vcc, 0, v5, vcc
	global_load_dword v54, v[8:9], off
	global_load_dword v59, v7, s[40:41]
	v_add_co_u32_e32 v8, vcc, 0x270000, v4
	v_add3_u32 v89, v88, v89, s42
	s_nop 0
	v_addc_co_u32_e32 v9, vcc, 0, v5, vcc
	global_load_dword v52, v[8:9], off
	global_load_dword v57, v7, s[44:45]
	v_add_co_u32_e32 v8, vcc, 0x280000, v4
	v_bfe_u32 v88, v86, 16, 1
	s_nop 0
	v_addc_co_u32_e32 v9, vcc, 0, v5, vcc
	global_load_dword v50, v[8:9], off
	global_load_dword v55, v7, s[52:53]
	v_add_co_u32_e32 v8, vcc, 0x290000, v4
	v_fmac_f32_e32 v84, v86, v90
	s_nop 0
	v_addc_co_u32_e32 v9, vcc, 0, v5, vcc
	global_load_dword v48, v[8:9], off
	global_load_dword v53, v7, s[72:73]
	v_add_co_u32_e32 v8, vcc, 0x2a0000, v4
	v_fmac_f32_e32 v82, v84, v87
	s_nop 0
	v_addc_co_u32_e32 v9, vcc, 0, v5, vcc
	global_load_dword v46, v[8:9], off
	global_load_dword v51, v7, s[74:75]
	v_add_co_u32_e32 v8, vcc, 0x2b0000, v4
	v_fmac_f32_e32 v80, v82, v85
	s_nop 0
	v_addc_co_u32_e32 v9, vcc, 0, v5, vcc
	global_load_dword v44, v[8:9], off
	global_load_dword v49, v7, s[76:77]
	v_add_co_u32_e32 v8, vcc, 0x2c0000, v4
	v_fmac_f32_e32 v78, v80, v83
	s_nop 0
	v_addc_co_u32_e32 v9, vcc, 0, v5, vcc
	global_load_dword v42, v[8:9], off
	global_load_dword v47, v7, s[84:85]
	v_add_co_u32_e32 v8, vcc, 0x2d0000, v4
	s_waitcnt vmcnt(0)
	v_fmac_f32_e32 v76, v78, v81
	v_addc_co_u32_e32 v9, vcc, 0, v5, vcc
	global_load_dword v40, v[8:9], off
	global_load_dword v45, v7, s[92:93]
	v_add_co_u32_e32 v8, vcc, 0x2e0000, v4
	v_fmac_f32_e32 v74, v76, v79
	s_nop 0
	v_addc_co_u32_e32 v9, vcc, 0, v5, vcc
	global_load_dword v38, v[8:9], off
	global_load_dword v43, v7, s[2:3]
	v_add_co_u32_e32 v8, vcc, 0x2f0000, v4
	v_fmac_f32_e32 v72, v74, v77
	s_nop 0
	v_addc_co_u32_e32 v9, vcc, 0, v5, vcc
	global_load_dword v36, v[8:9], off
	global_load_dword v41, v7, s[56:57]
	v_add_co_u32_e32 v8, vcc, 0x300000, v4
	v_fmac_f32_e32 v70, v72, v75
	s_nop 0
	v_addc_co_u32_e32 v9, vcc, 0, v5, vcc
	global_load_dword v34, v[8:9], off
	global_load_dword v39, v7, s[58:59]
	v_add_co_u32_e32 v8, vcc, 0x310000, v4
	v_fmac_f32_e32 v68, v70, v73
	s_nop 0
	v_addc_co_u32_e32 v9, vcc, 0, v5, vcc
	global_load_dword v32, v[8:9], off
	global_load_dword v37, v7, s[66:67]
	v_add_co_u32_e32 v8, vcc, 0x320000, v4
	v_fmac_f32_e32 v66, v68, v71
	s_nop 0
	v_addc_co_u32_e32 v9, vcc, 0, v5, vcc
	global_load_dword v30, v[8:9], off
	global_load_dword v35, v7, s[68:69]
	v_add_co_u32_e32 v8, vcc, 0x330000, v4
	v_fmac_f32_e32 v64, v66, v69
	s_nop 0
	v_addc_co_u32_e32 v9, vcc, 0, v5, vcc
	global_load_dword v28, v[8:9], off
	global_load_dword v33, v7, s[4:5]
	v_add_co_u32_e32 v8, vcc, 0x340000, v4
	v_fmac_f32_e32 v62, v64, v67
	s_nop 0
	v_addc_co_u32_e32 v9, vcc, 0, v5, vcc
	global_load_dword v26, v[8:9], off
	global_load_dword v31, v7, s[10:11]
	v_add_co_u32_e32 v8, vcc, 0x350000, v4
	v_fmac_f32_e32 v60, v62, v65
	s_nop 0
	v_addc_co_u32_e32 v9, vcc, 0, v5, vcc
	global_load_dword v24, v[8:9], off
	global_load_dword v29, v7, s[12:13]
	v_add_co_u32_e32 v8, vcc, 0x360000, v4
	v_fmac_f32_e32 v58, v60, v63
	s_nop 0
	v_addc_co_u32_e32 v9, vcc, 0, v5, vcc
	global_load_dword v23, v[8:9], off
	global_load_dword v27, v7, s[14:15]
	v_add_co_u32_e32 v8, vcc, 0x370000, v4
	v_fmac_f32_e32 v56, v58, v61
	s_nop 0
	v_addc_co_u32_e32 v9, vcc, 0, v5, vcc
	global_load_dword v20, v[8:9], off
	global_load_dword v25, v7, s[16:17]
	v_add_co_u32_e32 v8, vcc, 0x380000, v4
	v_fmac_f32_e32 v54, v56, v59
	s_nop 0
	v_addc_co_u32_e32 v9, vcc, 0, v5, vcc
	global_load_dword v19, v[8:9], off
	global_load_dword v22, v7, s[18:19]
	v_add_co_u32_e32 v8, vcc, 0x390000, v4
	v_fmac_f32_e32 v52, v54, v57
	s_nop 0
	v_addc_co_u32_e32 v9, vcc, 0, v5, vcc
	global_load_dword v16, v[8:9], off
	global_load_dword v21, v7, s[20:21]
	v_add_co_u32_e32 v8, vcc, 0x3a0000, v4
	v_fmac_f32_e32 v50, v52, v55
	s_nop 0
	v_addc_co_u32_e32 v9, vcc, 0, v5, vcc
	global_load_dword v15, v[8:9], off
	global_load_dword v18, v7, s[22:23]
	v_add_co_u32_e32 v8, vcc, 0x3b0000, v4
	v_fmac_f32_e32 v48, v50, v53
	s_nop 0
	v_addc_co_u32_e32 v9, vcc, 0, v5, vcc
	global_load_dword v12, v[8:9], off
	global_load_dword v17, v7, s[24:25]
	v_add_co_u32_e32 v8, vcc, 0x3c0000, v4
	v_fmac_f32_e32 v46, v48, v51
	s_nop 0
	v_addc_co_u32_e32 v9, vcc, 0, v5, vcc
	global_load_dword v11, v[8:9], off
	global_load_dword v14, v7, s[26:27]
	v_add_co_u32_e32 v8, vcc, 0x3d0000, v4
	v_fmac_f32_e32 v44, v46, v49
	s_nop 0
	v_addc_co_u32_e32 v9, vcc, 0, v5, vcc
	v_add_co_u32_e32 v134, vcc, 0x3e0000, v4
	global_load_dword v9, v[8:9], off
	s_nop 0
	global_load_dword v13, v7, s[28:29]
	v_addc_co_u32_e32 v135, vcc, 0, v5, vcc
	v_add_co_u32_e32 v4, vcc, 0x3f0000, v4
	global_load_dword v8, v[134:135], off
	global_load_dword v10, v7, s[30:31]
	v_addc_co_u32_e32 v5, vcc, 0, v5, vcc
	v_add_co_u32_e32 v134, vcc, 0x8000, v2
	global_load_dword v4, v[4:5], off
	s_nop 0
	global_load_dword v5, v7, s[34:35]
	v_addc_co_u32_e32 v135, vcc, 0, v3, vcc
	v_add_co_u32_e32 v132, vcc, s43, v2
	global_store_short_d16_hi v[134:135], v133, off
	s_nop 0
	v_addc_co_u32_e32 v133, vcc, 0, v3, vcc
	global_store_short_d16_hi v[132:133], v130, off
	v_add_co_u32_e32 v130, vcc, 0x18000, v2
	s_mov_b32 s43, 0x20000
	s_nop 0
	v_addc_co_u32_e32 v131, vcc, 0, v3, vcc
	global_store_short_d16_hi v[130:131], v128, off
	v_add_co_u32_e32 v128, vcc, s43, v2
	s_mov_b32 s43, 0x30000
	s_nop 0
	v_addc_co_u32_e32 v129, vcc, 0, v3, vcc
	global_store_short_d16_hi v[128:129], v126, off
	v_add_co_u32_e32 v126, vcc, 0x28000, v2
	v_fmac_f32_e32 v42, v44, v47
	s_nop 0
	v_addc_co_u32_e32 v127, vcc, 0, v3, vcc
	global_store_short_d16_hi v[126:127], v124, off
	v_add_co_u32_e32 v124, vcc, s43, v2
	s_mov_b32 s43, 0x40000
	s_nop 0
	v_addc_co_u32_e32 v125, vcc, 0, v3, vcc
	global_store_short_d16_hi v[124:125], v122, off
	v_add_co_u32_e32 v122, vcc, 0x38000, v2
	s_waitcnt vmcnt(0)
	v_fmac_f32_e32 v40, v42, v45
	v_addc_co_u32_e32 v123, vcc, 0, v3, vcc
	global_store_short_d16_hi v[122:123], v120, off
	v_add_co_u32_e32 v120, vcc, s43, v2
	s_mov_b32 s43, 0x50000
	s_nop 0
	v_addc_co_u32_e32 v121, vcc, 0, v3, vcc
	global_store_short_d16_hi v[120:121], v118, off
	v_add_co_u32_e32 v118, vcc, 0x48000, v2
	v_fmac_f32_e32 v38, v40, v43
	s_nop 0
	v_addc_co_u32_e32 v119, vcc, 0, v3, vcc
	global_store_short_d16_hi v[118:119], v116, off
	v_add_co_u32_e32 v116, vcc, s43, v2
	s_mov_b32 s43, 0x60000
	s_nop 0
	v_addc_co_u32_e32 v117, vcc, 0, v3, vcc
	global_store_short_d16_hi v[116:117], v113, off
	v_add_co_u32_e32 v116, vcc, 0x58000, v2
	v_fmac_f32_e32 v36, v38, v41
	s_nop 0
	v_addc_co_u32_e32 v117, vcc, 0, v3, vcc
	v_add_co_u32_e32 v114, vcc, s43, v2
	s_mov_b32 s43, 0x70000
	s_nop 0
	v_addc_co_u32_e32 v115, vcc, 0, v3, vcc
	v_add_co_u32_e32 v112, vcc, 0x68000, v2
	global_store_short_d16_hi v[116:117], v111, off
	s_nop 0
	v_addc_co_u32_e32 v113, vcc, 0, v3, vcc
	v_add_co_u32_e32 v110, vcc, s43, v2
	global_store_short_d16_hi v[114:115], v109, off
	s_nop 0
	v_addc_co_u32_e32 v111, vcc, 0, v3, vcc
	v_add_co_u32_e32 v108, vcc, 0x78000, v2
	s_mov_b32 s43, 0x80000
	s_nop 0
	v_addc_co_u32_e32 v109, vcc, 0, v3, vcc
	v_add_co_u32_e32 v106, vcc, s43, v2
	global_store_short_d16_hi v[112:113], v107, off
	s_nop 0
	v_addc_co_u32_e32 v107, vcc, 0, v3, vcc
	v_add_co_u32_e32 v104, vcc, 0x88000, v2
	global_store_short_d16_hi v[110:111], v105, off
	s_nop 0
	v_addc_co_u32_e32 v105, vcc, 0, v3, vcc
	s_mov_b32 s43, 0x90000
	v_add_co_u32_e32 v102, vcc, s43, v2
	global_store_short_d16_hi v[108:109], v103, off
	s_nop 0
	v_addc_co_u32_e32 v103, vcc, 0, v3, vcc
	v_add_co_u32_e32 v100, vcc, 0x98000, v2
	global_store_short_d16_hi v[106:107], v101, off
	s_nop 0
	v_addc_co_u32_e32 v101, vcc, 0, v3, vcc
	s_mov_b32 s43, 0xa0000
	v_add_co_u32_e32 v98, vcc, s43, v2
	global_store_short_d16_hi v[104:105], v99, off
	s_nop 0
	v_addc_co_u32_e32 v99, vcc, 0, v3, vcc
	v_add_co_u32_e32 v96, vcc, 0xa8000, v2
	global_store_short_d16_hi v[102:103], v97, off
	s_nop 0
	v_addc_co_u32_e32 v97, vcc, 0, v3, vcc
	s_mov_b32 s43, 0xb0000
	v_add_co_u32_e32 v94, vcc, s43, v2
	global_store_short_d16_hi v[100:101], v95, off
	s_nop 0
	v_addc_co_u32_e32 v95, vcc, 0, v3, vcc
	global_store_short_d16_hi v[96:97], v91, off
	v_add3_u32 v91, v86, v88, s42
	v_add_co_u32_e32 v88, vcc, 0xb8000, v2
	global_store_short_d16_hi v[94:95], v89, off
	s_nop 0
	v_addc_co_u32_e32 v89, vcc, 0, v3, vcc
	s_mov_b32 s43, 0xc0000
	global_store_short_d16_hi v[88:89], v91, off
	v_bfe_u32 v86, v84, 16, 1
	v_add_co_u32_e32 v88, vcc, s43, v2
	v_add3_u32 v86, v84, v86, s42
	s_nop 0
	v_addc_co_u32_e32 v89, vcc, 0, v3, vcc
	global_store_short_d16_hi v[88:89], v86, off
	v_bfe_u32 v84, v82, 16, 1
	v_add_co_u32_e32 v86, vcc, 0xc8000, v2
	v_add3_u32 v84, v82, v84, s42
	s_nop 0
	v_addc_co_u32_e32 v87, vcc, 0, v3, vcc
	s_mov_b32 s43, 0xd0000
	global_store_short_d16_hi v[86:87], v84, off
	v_bfe_u32 v82, v80, 16, 1
	v_add_co_u32_e32 v84, vcc, s43, v2
	v_add3_u32 v82, v80, v82, s42
	s_nop 0
	v_addc_co_u32_e32 v85, vcc, 0, v3, vcc
	global_store_short_d16_hi v[84:85], v82, off
	v_bfe_u32 v80, v78, 16, 1
	v_add_co_u32_e32 v82, vcc, 0xd8000, v2
	v_add3_u32 v80, v78, v80, s42
	s_nop 0
	v_addc_co_u32_e32 v83, vcc, 0, v3, vcc
	s_mov_b32 s43, 0xe0000
	global_store_short_d16_hi v[82:83], v80, off
	v_bfe_u32 v78, v76, 16, 1
	v_add_co_u32_e32 v80, vcc, s43, v2
	v_add3_u32 v78, v76, v78, s42
	s_nop 0
	v_addc_co_u32_e32 v81, vcc, 0, v3, vcc
	global_store_short_d16_hi v[80:81], v78, off
	v_bfe_u32 v76, v74, 16, 1
	v_add_co_u32_e32 v78, vcc, 0xe8000, v2
	v_add3_u32 v76, v74, v76, s42
	s_nop 0
	v_addc_co_u32_e32 v79, vcc, 0, v3, vcc
	s_mov_b32 s43, 0xf0000
	global_store_short_d16_hi v[78:79], v76, off
	v_bfe_u32 v74, v72, 16, 1
	v_add_co_u32_e32 v76, vcc, s43, v2
	v_add3_u32 v74, v72, v74, s42
	s_nop 0
	v_addc_co_u32_e32 v77, vcc, 0, v3, vcc
	global_store_short_d16_hi v[76:77], v74, off
	v_bfe_u32 v72, v70, 16, 1
	v_add_co_u32_e32 v74, vcc, 0xf8000, v2
	v_add3_u32 v72, v70, v72, s42
	s_nop 0
	v_addc_co_u32_e32 v75, vcc, 0, v3, vcc
	s_mov_b32 s43, 0x100000
	global_store_short_d16_hi v[74:75], v72, off
	v_bfe_u32 v70, v68, 16, 1
	v_add_co_u32_e32 v72, vcc, s43, v2
	v_add3_u32 v70, v68, v70, s42
	s_nop 0
	v_addc_co_u32_e32 v73, vcc, 0, v3, vcc
	global_store_short_d16_hi v[72:73], v70, off
	v_bfe_u32 v68, v66, 16, 1
	v_add_co_u32_e32 v70, vcc, 0x108000, v2
	v_add3_u32 v68, v66, v68, s42
	s_nop 0
	v_addc_co_u32_e32 v71, vcc, 0, v3, vcc
	s_mov_b32 s43, 0x110000
	global_store_short_d16_hi v[70:71], v68, off
	v_bfe_u32 v66, v64, 16, 1
	v_add_co_u32_e32 v68, vcc, s43, v2
	v_add3_u32 v66, v64, v66, s42
	s_nop 0
	v_addc_co_u32_e32 v69, vcc, 0, v3, vcc
	global_store_short_d16_hi v[68:69], v66, off
	v_bfe_u32 v64, v62, 16, 1
	v_add_co_u32_e32 v66, vcc, 0x118000, v2
	v_add3_u32 v64, v62, v64, s42
	s_nop 0
	v_addc_co_u32_e32 v67, vcc, 0, v3, vcc
	s_mov_b32 s43, 0x120000
	global_store_short_d16_hi v[66:67], v64, off
	v_bfe_u32 v62, v60, 16, 1
	v_add_co_u32_e32 v64, vcc, s43, v2
	v_add3_u32 v62, v60, v62, s42
	s_nop 0
	v_addc_co_u32_e32 v65, vcc, 0, v3, vcc
	global_store_short_d16_hi v[64:65], v62, off
	v_bfe_u32 v60, v58, 16, 1
	v_add_co_u32_e32 v62, vcc, 0x128000, v2
	v_add3_u32 v60, v58, v60, s42
	s_nop 0
	v_addc_co_u32_e32 v63, vcc, 0, v3, vcc
	s_mov_b32 s43, 0x130000
	global_store_short_d16_hi v[62:63], v60, off
	v_bfe_u32 v58, v56, 16, 1
	v_add_co_u32_e32 v60, vcc, s43, v2
	v_add3_u32 v58, v56, v58, s42
	s_nop 0
	v_addc_co_u32_e32 v61, vcc, 0, v3, vcc
	global_store_short_d16_hi v[60:61], v58, off
	v_bfe_u32 v56, v54, 16, 1
	v_add_co_u32_e32 v58, vcc, 0x138000, v2
	v_add3_u32 v56, v54, v56, s42
	s_nop 0
	v_addc_co_u32_e32 v59, vcc, 0, v3, vcc
	s_mov_b32 s43, 0x140000
	global_store_short_d16_hi v[58:59], v56, off
	v_bfe_u32 v54, v52, 16, 1
	v_add_co_u32_e32 v56, vcc, s43, v2
	v_add3_u32 v54, v52, v54, s42
	s_nop 0
	v_addc_co_u32_e32 v57, vcc, 0, v3, vcc
	global_store_short_d16_hi v[56:57], v54, off
	v_bfe_u32 v52, v50, 16, 1
	v_add_co_u32_e32 v54, vcc, 0x148000, v2
	v_add3_u32 v52, v50, v52, s42
	s_nop 0
	v_addc_co_u32_e32 v55, vcc, 0, v3, vcc
	s_mov_b32 s43, 0x150000
	global_store_short_d16_hi v[54:55], v52, off
	v_bfe_u32 v50, v48, 16, 1
	v_add_co_u32_e32 v52, vcc, s43, v2
	v_add3_u32 v50, v48, v50, s42
	s_nop 0
	v_addc_co_u32_e32 v53, vcc, 0, v3, vcc
	global_store_short_d16_hi v[52:53], v50, off
	v_bfe_u32 v48, v46, 16, 1
	v_add_co_u32_e32 v50, vcc, 0x158000, v2
	v_add3_u32 v48, v46, v48, s42
	s_nop 0
	v_addc_co_u32_e32 v51, vcc, 0, v3, vcc
	s_mov_b32 s43, 0x160000
	global_store_short_d16_hi v[50:51], v48, off
	v_bfe_u32 v46, v44, 16, 1
	v_add_co_u32_e32 v48, vcc, s43, v2
	v_add3_u32 v46, v44, v46, s42
	s_nop 0
	v_addc_co_u32_e32 v49, vcc, 0, v3, vcc
	global_store_short_d16_hi v[48:49], v46, off
	v_bfe_u32 v44, v42, 16, 1
	v_add_co_u32_e32 v46, vcc, 0x168000, v2
	v_add3_u32 v44, v42, v44, s42
	s_nop 0
	v_addc_co_u32_e32 v47, vcc, 0, v3, vcc
	s_mov_b32 s43, 0x170000
	global_store_short_d16_hi v[46:47], v44, off
	v_bfe_u32 v42, v40, 16, 1
	v_add_co_u32_e32 v44, vcc, s43, v2
	v_add3_u32 v42, v40, v42, s42
	s_nop 0
	v_addc_co_u32_e32 v45, vcc, 0, v3, vcc
	global_store_short_d16_hi v[44:45], v42, off
	v_bfe_u32 v40, v38, 16, 1
	v_add_co_u32_e32 v42, vcc, 0x178000, v2
	v_add3_u32 v40, v38, v40, s42
	s_nop 0
	v_addc_co_u32_e32 v43, vcc, 0, v3, vcc
	s_mov_b32 s43, 0x180000
	global_store_short_d16_hi v[42:43], v40, off
	v_bfe_u32 v38, v36, 16, 1
	v_add_co_u32_e32 v40, vcc, s43, v2
	v_add3_u32 v38, v36, v38, s42
	s_nop 0
	v_addc_co_u32_e32 v41, vcc, 0, v3, vcc
	v_fmac_f32_e32 v34, v36, v39
	global_store_short_d16_hi v[40:41], v38, off
	v_bfe_u32 v36, v34, 16, 1
	v_add_co_u32_e32 v38, vcc, 0x188000, v2
	v_add3_u32 v36, v34, v36, s42
	s_nop 0
	v_addc_co_u32_e32 v39, vcc, 0, v3, vcc
	v_fmac_f32_e32 v32, v34, v37
	s_mov_b32 s43, 0x190000
	global_store_short_d16_hi v[38:39], v36, off
	v_bfe_u32 v34, v32, 16, 1
	v_add_co_u32_e32 v36, vcc, s43, v2
	v_add3_u32 v34, v32, v34, s42
	s_nop 0
	v_addc_co_u32_e32 v37, vcc, 0, v3, vcc
	v_fmac_f32_e32 v30, v32, v35
	global_store_short_d16_hi v[36:37], v34, off
	v_bfe_u32 v32, v30, 16, 1
	v_add_co_u32_e32 v34, vcc, 0x198000, v2
	v_add3_u32 v32, v30, v32, s42
	s_nop 0
	v_addc_co_u32_e32 v35, vcc, 0, v3, vcc
	v_fmac_f32_e32 v28, v30, v33
	s_mov_b32 s43, 0x1a0000
	global_store_short_d16_hi v[34:35], v32, off
	v_bfe_u32 v30, v28, 16, 1
	v_add_co_u32_e32 v32, vcc, s43, v2
	v_add3_u32 v30, v28, v30, s42
	s_nop 0
	v_addc_co_u32_e32 v33, vcc, 0, v3, vcc
	v_fmac_f32_e32 v26, v28, v31
	global_store_short_d16_hi v[32:33], v30, off
	v_bfe_u32 v28, v26, 16, 1
	v_add_co_u32_e32 v30, vcc, 0x1a8000, v2
	v_add3_u32 v28, v26, v28, s42
	s_nop 0
	v_addc_co_u32_e32 v31, vcc, 0, v3, vcc
	v_fmac_f32_e32 v24, v26, v29
	s_mov_b32 s43, 0x1b0000
	global_store_short_d16_hi v[30:31], v28, off
	v_bfe_u32 v26, v24, 16, 1
	v_add_co_u32_e32 v28, vcc, s43, v2
	v_add3_u32 v26, v24, v26, s42
	s_nop 0
	v_addc_co_u32_e32 v29, vcc, 0, v3, vcc
	v_fmac_f32_e32 v23, v24, v27
	global_store_short_d16_hi v[28:29], v26, off
	v_bfe_u32 v24, v23, 16, 1
	v_add_co_u32_e32 v26, vcc, 0x1b8000, v2
	v_add3_u32 v24, v23, v24, s42
	s_nop 0
	v_addc_co_u32_e32 v27, vcc, 0, v3, vcc
	s_mov_b32 s43, 0x1c0000
	global_store_short_d16_hi v[26:27], v24, off
	v_fmac_f32_e32 v20, v23, v25
	v_add_co_u32_e32 v24, vcc, s43, v2
	v_bfe_u32 v23, v20, 16, 1
	s_nop 0
	v_addc_co_u32_e32 v25, vcc, 0, v3, vcc
	v_fmac_f32_e32 v19, v20, v22
	v_add3_u32 v23, v20, v23, s42
	v_bfe_u32 v20, v19, 16, 1
	v_add_co_u32_e32 v22, vcc, 0x1c8000, v2
	global_store_short_d16_hi v[24:25], v23, off
	v_add3_u32 v20, v19, v20, s42
	v_addc_co_u32_e32 v23, vcc, 0, v3, vcc
	s_mov_b32 s43, 0x1d0000
	global_store_short_d16_hi v[22:23], v20, off
	v_fmac_f32_e32 v16, v19, v21
	v_add_co_u32_e32 v20, vcc, s43, v2
	v_bfe_u32 v19, v16, 16, 1
	s_nop 0
	v_addc_co_u32_e32 v21, vcc, 0, v3, vcc
	v_fmac_f32_e32 v15, v16, v18
	v_add3_u32 v19, v16, v19, s42
	v_bfe_u32 v16, v15, 16, 1
	v_add_co_u32_e32 v18, vcc, 0x1d8000, v2
	global_store_short_d16_hi v[20:21], v19, off
	v_add3_u32 v16, v15, v16, s42
	v_addc_co_u32_e32 v19, vcc, 0, v3, vcc
	s_mov_b32 s43, 0x1e0000
	global_store_short_d16_hi v[18:19], v16, off
	v_fmac_f32_e32 v12, v15, v17
	v_add_co_u32_e32 v16, vcc, s43, v2
	v_bfe_u32 v15, v12, 16, 1
	s_nop 0
	v_addc_co_u32_e32 v17, vcc, 0, v3, vcc
	v_fmac_f32_e32 v11, v12, v14
	v_add3_u32 v15, v12, v15, s42
	v_bfe_u32 v12, v11, 16, 1
	v_add_co_u32_e32 v14, vcc, 0x1e8000, v2
	global_store_short_d16_hi v[16:17], v15, off
	v_add3_u32 v12, v11, v12, s42
	v_addc_co_u32_e32 v15, vcc, 0, v3, vcc
	s_mov_b32 s43, 0x1f0000
	global_store_short_d16_hi v[14:15], v12, off
	v_add_co_u32_e32 v12, vcc, s43, v2
	v_fmac_f32_e32 v9, v11, v13
	s_nop 0
	v_addc_co_u32_e32 v13, vcc, 0, v3, vcc
	global_store_short v[2:3], v7, off
	v_bfe_u32 v11, v9, 16, 1
	v_fmac_f32_e32 v8, v9, v10
	v_add_co_u32_e32 v2, vcc, 0x1f8000, v2
	v_add3_u32 v11, v9, v11, s42
	v_bfe_u32 v9, v8, 16, 1
	v_addc_co_u32_e32 v3, vcc, 0, v3, vcc
	v_add3_u32 v9, v8, v9, s42
	v_fmac_f32_e32 v4, v8, v5
	s_mov_b32 s43, 64
	s_and_b64 vcc, exec, s[0:1]
	global_store_short_d16_hi v[98:99], v93, off
	global_store_short_d16_hi v[12:13], v11, off
	global_store_short_d16_hi v[2:3], v9, off
	global_store_dword v[0:1], v4, off
	s_cbranch_vccz .LBB0_1057
	s_cmp_eq_u32 s101, 1
	s_cselect_b32 s33, 0x10000, s33
.Lc_items_first:
	v_readlane_b32 s0, v238, 3
	s_add_i32 s33, s0, s33
	v_readlane_b32 s96, v238, 5
	v_readlane_b32 s64, v239, 51
	v_readlane_b32 s80, v238, 36
	s_cmpk_gt_i32 s33, 0x83f
	v_readlane_b32 s92, v238, 38
	v_readlane_b32 s94, v238, 40
	v_readlane_b32 s87, v238, 4
	v_readlane_b32 s97, v238, 6
	v_readlane_b32 s84, v238, 7
	v_readlane_b32 s65, v239, 52
	v_readlane_b32 s68, v239, 55
	v_readlane_b32 s69, v239, 56
	v_readlane_b32 s76, v239, 63
	v_readlane_b32 s77, v238, 0
	v_readlane_b32 s81, v238, 37
	v_readlane_b32 s93, v238, 39
	v_readlane_b32 s95, v238, 41
	v_readlane_b32 s66, v239, 53
	v_readlane_b32 s67, v239, 54
	v_readlane_b32 s70, v239, 57
	v_readlane_b32 s71, v239, 58
	v_readlane_b32 s72, v239, 59
	v_readlane_b32 s73, v239, 60
	v_readlane_b32 s74, v239, 61
	v_readlane_b32 s75, v239, 62
	v_readlane_b32 s78, v238, 1
	v_readlane_b32 s79, v238, 2
	s_cbranch_scc1 .LBB0_1221
	v_lshrrev_b32_e32 v1, 5, v6
	v_lshlrev_b32_e32 v66, 2, v1
	v_lshlrev_b32_e32 v0, 3, v1
	v_lshlrev_b32_e32 v64, 4, v1
	v_add_u32_e32 v1, 24, v66
	v_and_b32_e32 v5, 64, v6
	v_lshrrev_b32_e32 v99, 5, v1
	v_and_b32_e32 v100, 28, v1
	v_add_u32_e32 v1, 40, v66
	v_xor_b32_e32 v3, 32, v6
	v_add_u32_e32 v5, 64, v5
	v_and_b32_e32 v101, 28, v1
	v_add_u32_e32 v1, 56, v66
	s_add_u32 s2, s90, 0x37971600
	v_mov_b32_e32 v65, 0
	v_cmp_lt_i32_e32 vcc, v3, v5
	v_lshrrev_b32_e32 v102, 5, v1
	v_and_b32_e32 v103, 28, v1
	v_add_u32_e32 v1, 0x48, v66
	s_addc_u32 s3, s91, 0
	v_and_b32_e32 v67, 31, v6
	v_cndmask_b32_e32 v3, v6, v3, vcc
	v_and_b32_e32 v104, 28, v1
	v_add_u32_e32 v1, 0x58, v66
	v_lshl_add_u64 v[6:7], s[90:91], 0, v[64:65]
	s_mov_b64 s[0:1], 0x52149600
	s_add_u32 s8, s90, 0x3b971600
	v_lshlrev_b32_e32 v2, 7, v67
	v_readlane_b32 s12, v239, 19
	v_lshrrev_b32_e32 v105, 5, v1
	v_and_b32_e32 v106, 28, v1
	v_add_u32_e32 v1, 0x68, v66
	v_lshl_add_u64 v[70:71], v[6:7], 0, s[0:1]
	v_readlane_b32 s1, v238, 3
	s_addc_u32 s9, s91, 0
	v_or_b32_e32 v4, 0x1000, v2
	v_or_b32_e32 v8, 0x2000, v2
	v_or_b32_e32 v10, 0x3000, v2
	v_readlane_b32 s13, v239, 20
	v_readlane_b32 s14, v239, 21
	v_readlane_b32 s15, v239, 22
	v_readlane_b32 s16, v239, 23
	v_readlane_b32 s17, v239, 24
	v_readlane_b32 s18, v239, 25
	v_readlane_b32 s19, v239, 26
	v_readlane_b32 s20, v239, 27
	v_readlane_b32 s21, v239, 28
	v_readlane_b32 s22, v239, 29
	v_readlane_b32 s23, v239, 30
	v_and_b32_e32 v107, 28, v1
	v_add_u32_e32 v1, 0x78, v66
	s_lshl_b32 s0, s94, 8
	s_lshl_b32 s1, s1, 5
	v_lshlrev_b32_e32 v96, 2, v3
	v_lshl_add_u64 v[68:69], s[16:17], 0, v[64:65]
	v_add_u32_e32 v97, 8, v66
	v_or_b32_e32 v98, 16, v66
	v_lshrrev_b32_e32 v108, 5, v1
	v_and_b32_e32 v109, 28, v1
	s_lshl_b32 s34, s92, 3
	s_add_i32 s35, s0, s1
	s_lshl_b32 s36, s92, 8
	s_movk_i32 s37, 0x7f7
	s_movk_i32 s38, 0x1ff
	s_mov_b64 s[10:11], 0x400
	s_mov_b32 s39, 0x8000
	s_mov_b32 s40, 0x80808081
	s_movk_i32 s41, 0xff
	s_mov_b64 s[12:13], 0x800
	v_lshlrev_b32_e32 v72, 2, v0
	v_lshlrev_b32_e32 v74, 1, v2
	v_lshlrev_b32_e32 v76, 1, v4
	v_lshlrev_b32_e32 v78, 1, v8
	v_lshlrev_b32_e32 v80, 1, v10
	s_mov_b64 s[14:15], 0x60
	s_mov_b64 s[16:17], 0x80
	s_mov_b64 s[18:19], 0xa0
	s_mov_b64 s[20:21], 0xc0
	s_mov_b64 s[22:23], 0xe0
	v_mov_b32_e32 v110, 0x358637bd
	s_mov_b32 s42, 0x800000
	s_mov_b32 s43, 0x26cf1600
	s_movk_i32 s44, 0x7fff
	v_or3_b32 v83, 0, 0, 0
	v_mov_b32_e32 v111, 0x1232b600
	v_mov_b32_e32 v112, 0x1132b600
	v_readlane_b32 s24, v239, 31
	v_readlane_b32 s25, v239, 32
	v_readlane_b32 s26, v239, 33
	v_readlane_b32 s27, v239, 34
	s_branch .LBB0_1061

.LBB0_1220:
	v_readlane_b32 s64, v239, 51
	v_readlane_b32 s65, v239, 52
	v_readlane_b32 s68, v239, 55
	v_readlane_b32 s69, v239, 56
	v_readlane_b32 s76, v239, 63
	v_readlane_b32 s77, v238, 0
	v_readlane_b32 s66, v239, 53
	v_readlane_b32 s67, v239, 54
	v_readlane_b32 s70, v239, 57
	v_readlane_b32 s71, v239, 58
	v_readlane_b32 s72, v239, 59
	v_readlane_b32 s73, v239, 60
	v_readlane_b32 s74, v239, 61
	v_readlane_b32 s75, v239, 62
	v_readlane_b32 s78, v238, 1
	v_readlane_b32 s79, v238, 2
	s_bitcmp1_b32 s94, 0
	s_cbranch_scc0 .LBB0_1221
	s_cmp_lg_u32 s101, 0
	s_cbranch_scc1 .LBB0_1221
	s_mov_b32 s101, 1
	s_mov_b32 s3, s95
	s_branch .Lcfin_pre
